# merge phase epilogue: the 32 gate loads of a branch issued together after the K loop's last MFMAs (were 16 serialized load-pair round trips)
# speedup vs baseline: 1.0418x; 1.0093x over previous
; DI void gemm_kloop64(const bf16_t* __restrict__ A, int lda, const bf16_t* __restrict__ B, int ldb, int K, bf16_t* sm,
;                      f32x4 (&acc)[2][4]) {
;     ...
;   __syncthreads();
;   GLOAD(ra0, rb0, 0)
;   GLOAD(ra1, rb1, 64)
;   SSTORE(ra0, rb0, 0)
;   __syncthreads();
;   for (int kt = 0; kt < nk - 2; kt += 2) {
;     GLOAD(ra0, rb0, (kt + 2) << 6)
;     COMPUTE(0)
;     SSTORE(ra1, rb1, 1)
;     __syncthreads();
;     GLOAD(ra1, rb1, (kt + 3) << 6)
;     COMPUTE(1)
;     SSTORE(ra0, rb0, 0)
;     __syncthreads();
;   }
;   COMPUTE(0)
;   SSTORE(ra1, rb1, 1)
;   __syncthreads();
;   COMPUTE(1)
;   __syncthreads();
.LBB0_1719:
	s_load_dwordx2 s[10:11], s[10:11], 0x0
	v_mov_b32_e32 v90, v182
	v_mov_b32_e32 v5, v164
	v_lshlrev_b32_e32 v4, 3, v90
	v_ashrrev_i32_e32 v69, 3, v90
	v_and_b32_e32 v91, 56, v4
	s_waitcnt lgkmcnt(0)
	s_add_u32 s10, s10, s4
	v_lshl_or_b32 v4, v69, 9, v91
	s_addc_u32 s11, s11, s5
	v_lshlrev_b64 v[20:21], 1, v[4:5]
	v_lshl_add_u64 v[92:93], s[10:11], 0, v[20:21]
	v_add_co_u32_e32 v94, vcc, s84, v92
	s_nop 1
	v_addc_co_u32_e32 v95, vcc, 0, v93, vcc
	v_add_co_u32_e32 v96, vcc, s85, v92
	s_barrier
	global_load_dwordx4 v[4:7], v[92:93], off
	global_load_dwordx4 v[8:11], v[94:95], off
	v_addc_co_u32_e32 v97, vcc, 0, v93, vcc
	v_add_co_u32_e32 v98, vcc, s55, v92
	global_load_dwordx4 v[12:15], v[96:97], off
	s_nop 0
	v_addc_co_u32_e32 v99, vcc, 0, v93, vcc
	global_load_dwordx4 v[16:19], v[98:99], off
	v_lshl_add_u64 v[100:101], s[6:7], 0, v[20:21]
	global_load_dwordx4 v[20:23], v[100:101], off
	v_add_co_u32_e32 v102, vcc, s84, v100
	v_mul_lo_u32 v69, v69, s54
	s_nop 0
	v_addc_co_u32_e32 v103, vcc, 0, v101, vcc
	global_load_dwordx4 v[24:27], v[102:103], off
	global_load_dwordx4 v[48:51], v[92:93], off offset:128
	global_load_dwordx4 v[44:47], v[94:95], off offset:128
	global_load_dwordx4 v[40:43], v[96:97], off offset:128
	global_load_dwordx4 v[36:39], v[98:99], off offset:128
	global_load_dwordx4 v[32:35], v[100:101], off offset:128
	global_load_dwordx4 v[28:31], v[102:103], off offset:128
	v_and_b32_e32 v107, 15, v90
	v_lshrrev_b32_e32 v108, 1, v90
	v_lshl_add_u32 v69, v91, 1, v69
	s_mov_b32 s10, 0xfffffe0
	s_add_i32 s15, s15, 1
	s_waitcnt vmcnt(11)
	ds_write_b128 v69, v[4:7]
	s_waitcnt vmcnt(10)
	ds_write_b128 v69, v[8:11] offset:4608
	s_waitcnt vmcnt(9)
	ds_write_b128 v69, v[12:15] offset:9216
	s_waitcnt vmcnt(8)
	ds_write_b128 v69, v[16:19] offset:13824
	s_waitcnt vmcnt(7)
	ds_write_b128 v69, v[20:23] offset:18432
	s_waitcnt vmcnt(6)
	ds_write_b128 v69, v[24:27] offset:23040
	v_and_or_b32 v5, v108, s10, v107
	v_and_b32_e32 v4, 48, v90
	v_mad_u64_u32 v[90:91], s[10:11], v5, s54, v[4:5]
	v_mul_u32_u24_e32 v5, 0x48, v107
	s_waitcnt lgkmcnt(0)
	s_barrier
	v_lshl_add_u32 v91, v5, 1, v4
	global_load_dwordx4 v[4:7], v[92:93], off offset:256
	global_load_dwordx4 v[8:11], v[94:95], off offset:256
	global_load_dwordx4 v[12:15], v[96:97], off offset:256
	global_load_dwordx4 v[16:19], v[98:99], off offset:256
	global_load_dwordx4 v[20:23], v[100:101], off offset:256
	global_load_dwordx4 v[24:27], v[102:103], off offset:256
	ds_read_b128 v[108:111], v90
	ds_read_b128 v[112:115], v90 offset:2304
	ds_read_b128 v[116:119], v91 offset:18432
	ds_read_b128 v[120:123], v91 offset:20736
	ds_read_b128 v[124:127], v91 offset:23040
	ds_read_b128 v[128:131], v91 offset:25344
	s_waitcnt lgkmcnt(3)
	v_mfma_f32_16x16x32_bf16 v[132:135], v[108:111], v[116:119], 0
	s_waitcnt lgkmcnt(2)
	v_mfma_f32_16x16x32_bf16 v[136:139], v[108:111], v[120:123], 0
	s_waitcnt lgkmcnt(1)
	v_mfma_f32_16x16x32_bf16 v[140:143], v[108:111], v[124:127], 0
	s_waitcnt lgkmcnt(0)
	v_mfma_f32_16x16x32_bf16 v[108:111], v[108:111], v[128:131], 0
	v_mfma_f32_16x16x32_bf16 v[116:119], v[112:115], v[116:119], 0
	v_mfma_f32_16x16x32_bf16 v[120:123], v[112:115], v[120:123], 0
	v_mfma_f32_16x16x32_bf16 v[124:127], v[112:115], v[124:127], 0
	v_mfma_f32_16x16x32_bf16 v[112:115], v[112:115], v[128:131], 0
	ds_read_b128 v[128:131], v90 offset:64
	ds_read_b128 v[144:147], v90 offset:2368
	ds_read_b128 v[148:151], v91 offset:18496
	ds_read_b128 v[152:155], v91 offset:20800
	ds_read_b128 v[156:159], v91 offset:23104
	ds_read_b128 v[160:163], v91 offset:25408
	s_waitcnt vmcnt(11)
	ds_write_b128 v69, v[48:51] offset:36864
	s_waitcnt vmcnt(10)
	ds_write_b128 v69, v[44:47] offset:41472
	s_waitcnt vmcnt(9)
	ds_write_b128 v69, v[40:43] offset:46080
	s_waitcnt vmcnt(8)
	ds_write_b128 v69, v[36:39] offset:50688
	s_waitcnt vmcnt(7)
	ds_write_b128 v69, v[32:35] offset:55296
	s_waitcnt vmcnt(6)
	ds_write_b128 v69, v[28:31] offset:59904
	s_waitcnt lgkmcnt(0)
	s_barrier
	global_load_dwordx4 v[28:31], v[92:93], off offset:384
	global_load_dwordx4 v[32:35], v[94:95], off offset:384
	global_load_dwordx4 v[36:39], v[96:97], off offset:384
	global_load_dwordx4 v[40:43], v[98:99], off offset:384
	global_load_dwordx4 v[44:47], v[100:101], off offset:384
	global_load_dwordx4 v[48:51], v[102:103], off offset:384
	v_mfma_f32_16x16x32_bf16 v[132:135], v[128:131], v[148:151], v[132:135]
	v_mfma_f32_16x16x32_bf16 v[136:139], v[128:131], v[152:155], v[136:139]
	v_mfma_f32_16x16x32_bf16 v[140:143], v[128:131], v[156:159], v[140:143]
	v_mfma_f32_16x16x32_bf16 v[108:111], v[128:131], v[160:163], v[108:111]
	v_mfma_f32_16x16x32_bf16 v[116:119], v[144:147], v[148:151], v[116:119]
	v_mfma_f32_16x16x32_bf16 v[120:123], v[144:147], v[152:155], v[120:123]
	v_mfma_f32_16x16x32_bf16 v[124:127], v[144:147], v[156:159], v[124:127]
	v_mfma_f32_16x16x32_bf16 v[112:115], v[144:147], v[160:163], v[112:115]
	ds_read_b128 v[128:131], v90 offset:36864
	ds_read_b128 v[144:147], v90 offset:39168
	ds_read_b128 v[148:151], v91 offset:55296
	ds_read_b128 v[152:155], v91 offset:57600
	ds_read_b128 v[156:159], v91 offset:59904
	ds_read_b128 v[160:163], v91 offset:62208
	s_waitcnt lgkmcnt(3)
	v_mfma_f32_16x16x32_bf16 v[132:135], v[128:131], v[148:151], v[132:135]
	s_waitcnt lgkmcnt(2)
	v_mfma_f32_16x16x32_bf16 v[136:139], v[128:131], v[152:155], v[136:139]
	s_waitcnt lgkmcnt(1)
	v_mfma_f32_16x16x32_bf16 v[140:143], v[128:131], v[156:159], v[140:143]
	s_waitcnt lgkmcnt(0)
	v_mfma_f32_16x16x32_bf16 v[108:111], v[128:131], v[160:163], v[108:111]
	v_mfma_f32_16x16x32_bf16 v[116:119], v[144:147], v[148:151], v[116:119]
	v_mfma_f32_16x16x32_bf16 v[120:123], v[144:147], v[152:155], v[120:123]
	v_mfma_f32_16x16x32_bf16 v[124:127], v[144:147], v[156:159], v[124:127]
	v_mfma_f32_16x16x32_bf16 v[112:115], v[144:147], v[160:163], v[112:115]
	ds_read_b128 v[128:131], v90 offset:36928
	ds_read_b128 v[144:147], v90 offset:39232
	ds_read_b128 v[148:151], v91 offset:55360
	ds_read_b128 v[152:155], v91 offset:57664
	ds_read_b128 v[156:159], v91 offset:59968
	ds_read_b128 v[160:163], v91 offset:62272
	s_waitcnt vmcnt(11)
	ds_write_b128 v69, v[4:7]
	s_waitcnt vmcnt(10)
	ds_write_b128 v69, v[8:11] offset:4608
	s_waitcnt vmcnt(9)
	ds_write_b128 v69, v[12:15] offset:9216
	s_waitcnt vmcnt(8)
	ds_write_b128 v69, v[16:19] offset:13824
	s_waitcnt vmcnt(7)
	ds_write_b128 v69, v[20:23] offset:18432
	s_waitcnt vmcnt(6)
	ds_write_b128 v69, v[24:27] offset:23040
	s_waitcnt lgkmcnt(0)
	s_barrier
; DI void gemm_kloop64(const bf16_t* __restrict__ A, int lda, const bf16_t* __restrict__ B, int ldb, int K, bf16_t* sm,
;                      f32x4 (&acc)[2][4]) {
;     ...
;   for (int kt = 0; kt < nk - 2; kt += 2) {
;     GLOAD(ra0, rb0, (kt + 2) << 6)
;     COMPUTE(0)
;     SSTORE(ra1, rb1, 1)
;     __syncthreads();
;     GLOAD(ra1, rb1, (kt + 3) << 6)
;     COMPUTE(1)
;     SSTORE(ra0, rb0, 0)
;     __syncthreads();
;   }
	global_load_dwordx4 v[4:7], v[92:93], off offset:512
	global_load_dwordx4 v[8:11], v[94:95], off offset:512
	global_load_dwordx4 v[12:15], v[96:97], off offset:512
	global_load_dwordx4 v[16:19], v[98:99], off offset:512
	global_load_dwordx4 v[20:23], v[100:101], off offset:512
	global_load_dwordx4 v[24:27], v[102:103], off offset:512
	v_mfma_f32_16x16x32_bf16 v[132:135], v[128:131], v[148:151], v[132:135]
	v_mfma_f32_16x16x32_bf16 v[136:139], v[128:131], v[152:155], v[136:139]
	v_mfma_f32_16x16x32_bf16 v[140:143], v[128:131], v[156:159], v[140:143]
	v_mfma_f32_16x16x32_bf16 v[108:111], v[128:131], v[160:163], v[108:111]
	v_mfma_f32_16x16x32_bf16 v[116:119], v[144:147], v[148:151], v[116:119]
	v_mfma_f32_16x16x32_bf16 v[120:123], v[144:147], v[152:155], v[120:123]
	v_mfma_f32_16x16x32_bf16 v[124:127], v[144:147], v[156:159], v[124:127]
	v_mfma_f32_16x16x32_bf16 v[112:115], v[144:147], v[160:163], v[112:115]
	ds_read_b128 v[128:131], v90
	ds_read_b128 v[144:147], v90 offset:2304
	ds_read_b128 v[148:151], v91 offset:18432
	ds_read_b128 v[152:155], v91 offset:20736
	ds_read_b128 v[156:159], v91 offset:23040
	ds_read_b128 v[160:163], v91 offset:25344
	s_waitcnt lgkmcnt(3)
	v_mfma_f32_16x16x32_bf16 v[132:135], v[128:131], v[148:151], v[132:135]
	s_waitcnt lgkmcnt(2)
	v_mfma_f32_16x16x32_bf16 v[136:139], v[128:131], v[152:155], v[136:139]
	s_waitcnt lgkmcnt(1)
	v_mfma_f32_16x16x32_bf16 v[140:143], v[128:131], v[156:159], v[140:143]
	s_waitcnt lgkmcnt(0)
	v_mfma_f32_16x16x32_bf16 v[108:111], v[128:131], v[160:163], v[108:111]
	v_mfma_f32_16x16x32_bf16 v[116:119], v[144:147], v[148:151], v[116:119]
	v_mfma_f32_16x16x32_bf16 v[120:123], v[144:147], v[152:155], v[120:123]
	v_mfma_f32_16x16x32_bf16 v[124:127], v[144:147], v[156:159], v[124:127]
	v_mfma_f32_16x16x32_bf16 v[112:115], v[144:147], v[160:163], v[112:115]
	ds_read_b128 v[128:131], v90 offset:64
	ds_read_b128 v[144:147], v90 offset:2368
	ds_read_b128 v[148:151], v91 offset:18496
	ds_read_b128 v[152:155], v91 offset:20800
	ds_read_b128 v[156:159], v91 offset:23104
	ds_read_b128 v[160:163], v91 offset:25408
	s_waitcnt vmcnt(11)
	ds_write_b128 v69, v[28:31] offset:36864
	s_waitcnt vmcnt(10)
	ds_write_b128 v69, v[32:35] offset:41472
	s_waitcnt vmcnt(9)
	ds_write_b128 v69, v[36:39] offset:46080
	s_waitcnt vmcnt(8)
	ds_write_b128 v69, v[40:43] offset:50688
	s_waitcnt vmcnt(7)
	ds_write_b128 v69, v[44:47] offset:55296
	s_waitcnt vmcnt(6)
	ds_write_b128 v69, v[48:51] offset:59904
	s_waitcnt lgkmcnt(0)
	s_barrier
	global_load_dwordx4 v[44:47], v[92:93], off offset:640
	global_load_dwordx4 v[48:51], v[94:95], off offset:640
	global_load_dwordx4 v[40:43], v[96:97], off offset:640
	global_load_dwordx4 v[32:35], v[98:99], off offset:640
	global_load_dwordx4 v[36:39], v[100:101], off offset:640
	global_load_dwordx4 v[28:31], v[102:103], off offset:640
	v_mfma_f32_16x16x32_bf16 v[132:135], v[128:131], v[148:151], v[132:135]
	v_mfma_f32_16x16x32_bf16 v[136:139], v[128:131], v[152:155], v[136:139]
	v_mfma_f32_16x16x32_bf16 v[140:143], v[128:131], v[156:159], v[140:143]
	v_mfma_f32_16x16x32_bf16 v[108:111], v[128:131], v[160:163], v[108:111]
	v_mfma_f32_16x16x32_bf16 v[116:119], v[144:147], v[148:151], v[116:119]
	v_mfma_f32_16x16x32_bf16 v[120:123], v[144:147], v[152:155], v[120:123]
	v_mfma_f32_16x16x32_bf16 v[124:127], v[144:147], v[156:159], v[124:127]
	v_mfma_f32_16x16x32_bf16 v[112:115], v[144:147], v[160:163], v[112:115]
	ds_read_b128 v[128:131], v90 offset:36864
	ds_read_b128 v[144:147], v90 offset:39168
	ds_read_b128 v[148:151], v91 offset:55296
	ds_read_b128 v[152:155], v91 offset:57600
	ds_read_b128 v[156:159], v91 offset:59904
	ds_read_b128 v[160:163], v91 offset:62208
	s_waitcnt lgkmcnt(3)
	v_mfma_f32_16x16x32_bf16 v[132:135], v[128:131], v[148:151], v[132:135]
	s_waitcnt lgkmcnt(2)
	v_mfma_f32_16x16x32_bf16 v[136:139], v[128:131], v[152:155], v[136:139]
	s_waitcnt lgkmcnt(1)
	v_mfma_f32_16x16x32_bf16 v[140:143], v[128:131], v[156:159], v[140:143]
	s_waitcnt lgkmcnt(0)
	v_mfma_f32_16x16x32_bf16 v[108:111], v[128:131], v[160:163], v[108:111]
	v_mfma_f32_16x16x32_bf16 v[116:119], v[144:147], v[148:151], v[116:119]
	v_mfma_f32_16x16x32_bf16 v[120:123], v[144:147], v[152:155], v[120:123]
	v_mfma_f32_16x16x32_bf16 v[124:127], v[144:147], v[156:159], v[124:127]
	v_mfma_f32_16x16x32_bf16 v[112:115], v[144:147], v[160:163], v[112:115]
	ds_read_b128 v[128:131], v90 offset:36928
	ds_read_b128 v[144:147], v90 offset:39232
	ds_read_b128 v[148:151], v91 offset:55360
	ds_read_b128 v[152:155], v91 offset:57664
	ds_read_b128 v[156:159], v91 offset:59968
	ds_read_b128 v[160:163], v91 offset:62272
	s_waitcnt vmcnt(11)
	ds_write_b128 v69, v[4:7]
	s_waitcnt vmcnt(10)
	ds_write_b128 v69, v[8:11] offset:4608
	s_waitcnt vmcnt(9)
	ds_write_b128 v69, v[12:15] offset:9216
	s_waitcnt vmcnt(8)
	ds_write_b128 v69, v[16:19] offset:13824
	s_waitcnt vmcnt(7)
	ds_write_b128 v69, v[20:23] offset:18432
	s_waitcnt vmcnt(6)
	ds_write_b128 v69, v[24:27] offset:23040
	s_waitcnt lgkmcnt(0)
	s_barrier
; DI void gemm_kloop64(const bf16_t* __restrict__ A, int lda, const bf16_t* __restrict__ B, int ldb, int K, bf16_t* sm,
;                      f32x4 (&acc)[2][4]) {
;     ...
;   for (int kt = 0; kt < nk - 2; kt += 2) {
;     GLOAD(ra0, rb0, (kt + 2) << 6)
;     COMPUTE(0)
;     SSTORE(ra1, rb1, 1)
;     __syncthreads();
;     GLOAD(ra1, rb1, (kt + 3) << 6)
;     COMPUTE(1)
;     SSTORE(ra0, rb0, 0)
;     __syncthreads();
;   }
	global_load_dwordx4 v[16:19], v[92:93], off offset:768
	global_load_dwordx4 v[20:23], v[94:95], off offset:768
	global_load_dwordx4 v[24:27], v[96:97], off offset:768
	global_load_dwordx4 v[4:7], v[98:99], off offset:768
	global_load_dwordx4 v[8:11], v[100:101], off offset:768
	global_load_dwordx4 v[12:15], v[102:103], off offset:768
	v_mfma_f32_16x16x32_bf16 v[132:135], v[128:131], v[148:151], v[132:135]
	v_mfma_f32_16x16x32_bf16 v[136:139], v[128:131], v[152:155], v[136:139]
	v_mfma_f32_16x16x32_bf16 v[140:143], v[128:131], v[156:159], v[140:143]
	v_mfma_f32_16x16x32_bf16 v[108:111], v[128:131], v[160:163], v[108:111]
	v_mfma_f32_16x16x32_bf16 v[116:119], v[144:147], v[148:151], v[116:119]
	v_mfma_f32_16x16x32_bf16 v[120:123], v[144:147], v[152:155], v[120:123]
	v_mfma_f32_16x16x32_bf16 v[124:127], v[144:147], v[156:159], v[124:127]
	v_mfma_f32_16x16x32_bf16 v[112:115], v[144:147], v[160:163], v[112:115]
	ds_read_b128 v[128:131], v90
	ds_read_b128 v[144:147], v90 offset:2304
	ds_read_b128 v[148:151], v91 offset:18432
	ds_read_b128 v[152:155], v91 offset:20736
	ds_read_b128 v[156:159], v91 offset:23040
	ds_read_b128 v[160:163], v91 offset:25344
	s_waitcnt lgkmcnt(3)
	v_mfma_f32_16x16x32_bf16 v[132:135], v[128:131], v[148:151], v[132:135]
	s_waitcnt lgkmcnt(2)
	v_mfma_f32_16x16x32_bf16 v[136:139], v[128:131], v[152:155], v[136:139]
	s_waitcnt lgkmcnt(1)
	v_mfma_f32_16x16x32_bf16 v[140:143], v[128:131], v[156:159], v[140:143]
	s_waitcnt lgkmcnt(0)
	v_mfma_f32_16x16x32_bf16 v[108:111], v[128:131], v[160:163], v[108:111]
	v_mfma_f32_16x16x32_bf16 v[116:119], v[144:147], v[148:151], v[116:119]
	v_mfma_f32_16x16x32_bf16 v[120:123], v[144:147], v[152:155], v[120:123]
	v_mfma_f32_16x16x32_bf16 v[124:127], v[144:147], v[156:159], v[124:127]
	v_mfma_f32_16x16x32_bf16 v[112:115], v[144:147], v[160:163], v[112:115]
	ds_read_b128 v[128:131], v90 offset:64
	ds_read_b128 v[144:147], v90 offset:2368
	ds_read_b128 v[148:151], v91 offset:18496
	ds_read_b128 v[152:155], v91 offset:20800
	ds_read_b128 v[156:159], v91 offset:23104
	ds_read_b128 v[160:163], v91 offset:25408
	s_waitcnt vmcnt(11)
	ds_write_b128 v69, v[44:47] offset:36864
	s_waitcnt vmcnt(10)
	ds_write_b128 v69, v[48:51] offset:41472
	s_waitcnt vmcnt(9)
	ds_write_b128 v69, v[40:43] offset:46080
	s_waitcnt vmcnt(8)
	ds_write_b128 v69, v[32:35] offset:50688
	s_waitcnt vmcnt(7)
	ds_write_b128 v69, v[36:39] offset:55296
	s_waitcnt vmcnt(6)
	ds_write_b128 v69, v[28:31] offset:59904
	s_waitcnt lgkmcnt(0)
	s_barrier
	global_load_dwordx4 v[40:43], v[92:93], off offset:896
	global_load_dwordx4 v[44:47], v[94:95], off offset:896
	global_load_dwordx4 v[48:51], v[96:97], off offset:896
	global_load_dwordx4 v[28:31], v[98:99], off offset:896
	global_load_dwordx4 v[32:35], v[100:101], off offset:896
	global_load_dwordx4 v[36:39], v[102:103], off offset:896
	v_mfma_f32_16x16x32_bf16 v[132:135], v[128:131], v[148:151], v[132:135]
	v_mfma_f32_16x16x32_bf16 v[136:139], v[128:131], v[152:155], v[136:139]
	v_mfma_f32_16x16x32_bf16 v[140:143], v[128:131], v[156:159], v[140:143]
	v_mfma_f32_16x16x32_bf16 v[108:111], v[128:131], v[160:163], v[108:111]
	v_mfma_f32_16x16x32_bf16 v[116:119], v[144:147], v[148:151], v[116:119]
	v_mfma_f32_16x16x32_bf16 v[120:123], v[144:147], v[152:155], v[120:123]
	v_mfma_f32_16x16x32_bf16 v[124:127], v[144:147], v[156:159], v[124:127]
	v_mfma_f32_16x16x32_bf16 v[112:115], v[144:147], v[160:163], v[112:115]
	ds_read_b128 v[92:95], v90 offset:36864
	ds_read_b128 v[96:99], v90 offset:39168
	ds_read_b128 v[100:103], v91 offset:55296
	ds_read_b128 v[128:131], v91 offset:57600
	ds_read_b128 v[144:147], v91 offset:59904
	ds_read_b128 v[148:151], v91 offset:62208
	s_waitcnt lgkmcnt(3)
	v_mfma_f32_16x16x32_bf16 v[132:135], v[92:95], v[100:103], v[132:135]
	s_waitcnt lgkmcnt(2)
	v_mfma_f32_16x16x32_bf16 v[136:139], v[92:95], v[128:131], v[136:139]
	s_waitcnt lgkmcnt(1)
	v_mfma_f32_16x16x32_bf16 v[140:143], v[92:95], v[144:147], v[140:143]
	s_waitcnt lgkmcnt(0)
	v_mfma_f32_16x16x32_bf16 v[92:95], v[92:95], v[148:151], v[108:111]
	v_mfma_f32_16x16x32_bf16 v[100:103], v[96:99], v[100:103], v[116:119]
	v_mfma_f32_16x16x32_bf16 v[108:111], v[96:99], v[128:131], v[120:123]
	v_mfma_f32_16x16x32_bf16 v[116:119], v[96:99], v[144:147], v[124:127]
	v_mfma_f32_16x16x32_bf16 v[96:99], v[96:99], v[148:151], v[112:115]
	s_nop 2
	ds_read_b128 v[112:115], v90 offset:36928
	ds_read_b128 v[120:123], v90 offset:39232
	ds_read_b128 v[124:127], v91 offset:55360
	ds_read_b128 v[128:131], v91 offset:57664
	ds_read_b128 v[144:147], v91 offset:59968
	ds_read_b128 v[148:151], v91 offset:62272
	s_waitcnt vmcnt(11)
	ds_write_b128 v69, v[16:19]
	s_waitcnt vmcnt(10)
	ds_write_b128 v69, v[20:23] offset:4608
	s_waitcnt vmcnt(9)
	ds_write_b128 v69, v[24:27] offset:9216
	s_waitcnt vmcnt(8)
	ds_write_b128 v69, v[4:7] offset:13824
	s_waitcnt vmcnt(7)
	ds_write_b128 v69, v[8:11] offset:18432
	s_waitcnt vmcnt(6)
	ds_write_b128 v69, v[12:15] offset:23040
	s_waitcnt lgkmcnt(0)
	s_barrier
; DI void gemm_kloop64(const bf16_t* __restrict__ A, int lda, const bf16_t* __restrict__ B, int ldb, int K, bf16_t* sm,
;                      f32x4 (&acc)[2][4]) {
;     ...
;   for (int kt = 0; kt < nk - 2; kt += 2) {
;     GLOAD(ra0, rb0, (kt + 2) << 6)
;     COMPUTE(0)
;     SSTORE(ra1, rb1, 1)
;     __syncthreads();
;     GLOAD(ra1, rb1, (kt + 3) << 6)
;     COMPUTE(1)
;     SSTORE(ra0, rb0, 0)
;     __syncthreads();
;   }
;   COMPUTE(0)
;   SSTORE(ra1, rb1, 1)
;   __syncthreads();
;   COMPUTE(1)
;   __syncthreads();
	ds_read_b128 v[4:7], v90
	ds_read_b128 v[8:11], v90 offset:2304
	ds_read_b128 v[12:15], v91 offset:18432
	ds_read_b128 v[16:19], v91 offset:20736
	ds_read_b128 v[20:23], v91 offset:23040
	ds_read_b128 v[24:27], v91 offset:25344
	v_mfma_f32_16x16x32_bf16 v[132:135], v[112:115], v[124:127], v[132:135]
	v_mfma_f32_16x16x32_bf16 v[136:139], v[112:115], v[128:131], v[136:139]
	v_mfma_f32_16x16x32_bf16 v[140:143], v[112:115], v[144:147], v[140:143]
	v_mfma_f32_16x16x32_bf16 v[92:95], v[112:115], v[148:151], v[92:95]
	v_mfma_f32_16x16x32_bf16 v[100:103], v[120:123], v[124:127], v[100:103]
	v_mfma_f32_16x16x32_bf16 v[108:111], v[120:123], v[128:131], v[108:111]
	v_mfma_f32_16x16x32_bf16 v[112:115], v[120:123], v[144:147], v[116:119]
	v_mfma_f32_16x16x32_bf16 v[96:99], v[120:123], v[148:151], v[96:99]
	s_waitcnt lgkmcnt(3)
	v_mfma_f32_16x16x32_bf16 v[116:119], v[4:7], v[12:15], v[132:135]
	s_waitcnt lgkmcnt(2)
	v_mfma_f32_16x16x32_bf16 v[120:123], v[4:7], v[16:19], v[136:139]
	s_waitcnt lgkmcnt(1)
	v_mfma_f32_16x16x32_bf16 v[124:127], v[4:7], v[20:23], v[140:143]
	s_waitcnt lgkmcnt(0)
	v_mfma_f32_16x16x32_bf16 v[4:7], v[4:7], v[24:27], v[92:95]
	v_mfma_f32_16x16x32_bf16 v[12:15], v[8:11], v[12:15], v[100:103]
	v_mfma_f32_16x16x32_bf16 v[16:19], v[8:11], v[16:19], v[108:111]
	v_mfma_f32_16x16x32_bf16 v[20:23], v[8:11], v[20:23], v[112:115]
	v_mfma_f32_16x16x32_bf16 v[8:11], v[8:11], v[24:27], v[96:99]
	ds_read_b128 v[24:27], v90 offset:64
	ds_read_b128 v[92:95], v90 offset:2368
	s_nop 0
	ds_read_b128 v[96:99], v91 offset:18496
	ds_read_b128 v[100:103], v91 offset:20800
	ds_read_b128 v[108:111], v91 offset:23104
	ds_read_b128 v[112:115], v91 offset:25408
	s_waitcnt vmcnt(5)
	ds_write_b128 v69, v[40:43] offset:36864
	s_waitcnt vmcnt(4)
	ds_write_b128 v69, v[44:47] offset:41472
	s_waitcnt vmcnt(3)
	ds_write_b128 v69, v[48:51] offset:46080
	s_waitcnt vmcnt(2)
	ds_write_b128 v69, v[28:31] offset:50688
	s_waitcnt vmcnt(1)
	ds_write_b128 v69, v[32:35] offset:55296
	s_waitcnt vmcnt(0)
	ds_write_b128 v69, v[36:39] offset:59904
	s_waitcnt lgkmcnt(0)
	v_mfma_f32_16x16x32_bf16 v[116:119], v[24:27], v[96:99], v[116:119]
	s_barrier
	v_mfma_f32_16x16x32_bf16 v[120:123], v[24:27], v[100:103], v[120:123]
	v_mfma_f32_16x16x32_bf16 v[124:127], v[24:27], v[108:111], v[124:127]
	v_mfma_f32_16x16x32_bf16 v[4:7], v[24:27], v[112:115], v[4:7]
	ds_read_b128 v[24:27], v90 offset:36864
	ds_read_b128 v[28:31], v90 offset:39168
	ds_read_b128 v[32:35], v91 offset:55296
	ds_read_b128 v[36:39], v91 offset:57600
	ds_read_b128 v[40:43], v91 offset:59904
	ds_read_b128 v[44:47], v91 offset:62208
	v_mfma_f32_16x16x32_bf16 v[12:15], v[92:95], v[96:99], v[12:15]
	v_mfma_f32_16x16x32_bf16 v[16:19], v[92:95], v[100:103], v[16:19]
	v_mfma_f32_16x16x32_bf16 v[20:23], v[92:95], v[108:111], v[20:23]
	v_mfma_f32_16x16x32_bf16 v[8:11], v[92:95], v[112:115], v[8:11]
	s_waitcnt lgkmcnt(3)
	v_mfma_f32_16x16x32_bf16 v[48:51], v[24:27], v[32:35], v[116:119]
	s_waitcnt lgkmcnt(2)
	v_mfma_f32_16x16x32_bf16 v[92:95], v[24:27], v[36:39], v[120:123]
	s_waitcnt lgkmcnt(1)
	v_mfma_f32_16x16x32_bf16 v[96:99], v[24:27], v[40:43], v[124:127]
	s_waitcnt lgkmcnt(0)
	v_mfma_f32_16x16x32_bf16 v[4:7], v[24:27], v[44:47], v[4:7]
	v_mfma_f32_16x16x32_bf16 v[12:15], v[28:31], v[32:35], v[12:15]
	v_mfma_f32_16x16x32_bf16 v[24:27], v[28:31], v[36:39], v[16:19]
	v_mfma_f32_16x16x32_bf16 v[20:23], v[28:31], v[40:43], v[20:23]
	v_mfma_f32_16x16x32_bf16 v[28:31], v[28:31], v[44:47], v[8:11]
	s_nop 2
	ds_read_b128 v[8:11], v90 offset:36928
	ds_read_b128 v[32:35], v90 offset:39232
	ds_read_b128 v[16:19], v91 offset:55360
	ds_read_b128 v[36:39], v91 offset:57664
	ds_read_b128 v[40:43], v91 offset:59968
	ds_read_b128 v[44:47], v91 offset:62272
	s_waitcnt lgkmcnt(0)
	s_barrier
; DI float bf2f(bf16_t b) { return __uint_as_float(((unsigned)b) << 16); }
; DI void gemm_kloop64(const bf16_t* __restrict__ A, int lda, const bf16_t* __restrict__ B, int ldb, int K, bf16_t* sm,
;                      f32x4 (&acc)[2][4]) {
;     ...
;   COMPUTE(0)
;   SSTORE(ra1, rb1, 1)
;   __syncthreads();
;   COMPUTE(1)
;   __syncthreads();
; DI void merge_phase(const Params& p, int l, char* smem) {
;     ...
; #pragma unroll
;       for (int i = 0; i < 2; i++)
; #pragma unroll
;         for (int r = 0; r < 4; r++) {
;           const int tok = mt * 128 + wave * 32 + i * 16 + g4 * 4 + r;
; #pragma unroll
;           for (int jn = 0; jn < 4; jn++) {
;             const int n = nt * 64 + jn * 16 + cl;
;             const float g = bf2f(p.G[(size_t)tok * 3072 + br * 1024 + n]);
;             tot[i][jn][r] += g * acc[i][jn][r];
;           }
;         }
	s_load_dwordx2 s[10:11], s[0:1], 0x160
	v_mfma_f32_16x16x32_bf16 v[48:51], v[8:11], v[16:19], v[48:51]
	v_mfma_f32_16x16x32_bf16 v[90:93], v[8:11], v[36:39], v[92:95]
	v_mfma_f32_16x16x32_bf16 v[94:97], v[8:11], v[40:43], v[96:99]
	v_mfma_f32_16x16x32_bf16 v[98:101], v[8:11], v[44:47], v[4:7]
	v_mfma_f32_16x16x32_bf16 v[8:11], v[32:35], v[40:43], v[20:23]
	v_mfma_f32_16x16x32_bf16 v[16:19], v[32:35], v[16:19], v[12:15]
	v_mfma_f32_16x16x32_bf16 v[12:15], v[32:35], v[36:39], v[24:27]
	v_mfma_f32_16x16x32_bf16 v[4:7], v[32:35], v[44:47], v[28:31]
	s_waitcnt lgkmcnt(0)
	v_lshl_add_u64 v[20:21], s[10:11], 0, v[86:87]
	v_lshl_add_u64 v[24:25], s[10:11], 0, v[88:89]
	v_lshl_add_u64 v[20:21], v[20:21], 0, s[8:9]
	v_lshl_add_u64 v[24:25], v[24:25], 0, s[8:9]
	v_add_co_u32_e32 v22, vcc, s94, v20
	s_nop 1
	v_addc_co_u32_e32 v23, vcc, 0, v21, vcc
	v_add_co_u32_e32 v26, vcc, s94, v24
	s_nop 1
	v_addc_co_u32_e32 v27, vcc, 0, v25, vcc
	global_load_ushort v220, v[20:21], off
	global_load_ushort v222, v[20:21], off offset:32
	global_load_ushort v224, v[20:21], off offset:64
	global_load_ushort v226, v[20:21], off offset:96
	global_load_ushort v221, v[22:23], off offset:2048
	global_load_ushort v223, v[22:23], off offset:2080
	global_load_ushort v225, v[22:23], off offset:2112
	global_load_ushort v227, v[22:23], off offset:2144
	global_load_ushort v236, v[24:25], off
	global_load_ushort v238, v[24:25], off offset:32
	global_load_ushort v240, v[24:25], off offset:64
	global_load_ushort v242, v[24:25], off offset:96
	global_load_ushort v237, v[26:27], off offset:2048
	global_load_ushort v239, v[26:27], off offset:2080
	global_load_ushort v241, v[26:27], off offset:2112
	global_load_ushort v243, v[26:27], off offset:2144
	v_add_co_u32_e32 v22, vcc, s70, v20
	s_nop 1
	v_addc_co_u32_e32 v23, vcc, 0, v21, vcc
	v_add_co_u32_e32 v28, vcc, s56, v20
	s_nop 1
	v_addc_co_u32_e32 v29, vcc, 0, v21, vcc
	v_add_co_u32_e32 v26, vcc, s70, v24
	s_nop 1
	v_addc_co_u32_e32 v27, vcc, 0, v25, vcc
	v_add_co_u32_e32 v30, vcc, s56, v24
	s_nop 1
	v_addc_co_u32_e32 v31, vcc, 0, v25, vcc
	global_load_ushort v228, v[22:23], off
	global_load_ushort v230, v[22:23], off offset:32
	global_load_ushort v232, v[22:23], off offset:64
	global_load_ushort v234, v[22:23], off offset:96
	global_load_ushort v229, v[28:29], off offset:2048
	global_load_ushort v231, v[28:29], off offset:2080
	global_load_ushort v233, v[28:29], off offset:2112
	global_load_ushort v235, v[28:29], off offset:2144
	global_load_ushort v244, v[26:27], off
	global_load_ushort v246, v[26:27], off offset:32
	global_load_ushort v248, v[26:27], off offset:64
	global_load_ushort v250, v[26:27], off offset:96
	global_load_ushort v245, v[30:31], off offset:2048
	global_load_ushort v247, v[30:31], off offset:2080
	global_load_ushort v249, v[30:31], off offset:2112
	global_load_ushort v251, v[30:31], off offset:2144
	s_waitcnt vmcnt(24)
	v_lshlrev_b32_e32 v220, 16, v220
	v_lshlrev_b32_e32 v221, 16, v221
	v_pk_fma_f32 v[84:85], v[48:49], v[220:221], v[84:85]
	v_lshlrev_b32_e32 v222, 16, v222
	v_lshlrev_b32_e32 v223, 16, v223
	v_pk_fma_f32 v[82:83], v[90:91], v[222:223], v[82:83]
	v_lshlrev_b32_e32 v224, 16, v224
	v_lshlrev_b32_e32 v225, 16, v225
	v_pk_fma_f32 v[80:81], v[94:95], v[224:225], v[80:81]
	v_lshlrev_b32_e32 v226, 16, v226
	v_lshlrev_b32_e32 v227, 16, v227
	v_pk_fma_f32 v[78:79], v[98:99], v[226:227], v[78:79]
	s_waitcnt vmcnt(16)
	v_lshlrev_b32_e32 v236, 16, v236
	v_lshlrev_b32_e32 v237, 16, v237
	v_pk_fma_f32 v[66:67], v[16:17], v[236:237], v[66:67]
	v_lshlrev_b32_e32 v238, 16, v238
	v_lshlrev_b32_e32 v239, 16, v239
	v_pk_fma_f32 v[64:65], v[12:13], v[238:239], v[64:65]
	v_lshlrev_b32_e32 v240, 16, v240
	v_lshlrev_b32_e32 v241, 16, v241
	v_pk_fma_f32 v[62:63], v[8:9], v[240:241], v[62:63]
	v_lshlrev_b32_e32 v242, 16, v242
	v_lshlrev_b32_e32 v243, 16, v243
	v_pk_fma_f32 v[58:59], v[4:5], v[242:243], v[58:59]
	s_waitcnt vmcnt(8)
	v_lshlrev_b32_e32 v228, 16, v228
	v_lshlrev_b32_e32 v229, 16, v229
	v_pk_fma_f32 v[76:77], v[50:51], v[228:229], v[76:77]
	v_lshlrev_b32_e32 v230, 16, v230
	v_lshlrev_b32_e32 v231, 16, v231
	v_pk_fma_f32 v[74:75], v[92:93], v[230:231], v[74:75]
	v_lshlrev_b32_e32 v232, 16, v232
	v_lshlrev_b32_e32 v233, 16, v233
	v_pk_fma_f32 v[72:73], v[96:97], v[232:233], v[72:73]
	v_lshlrev_b32_e32 v234, 16, v234
	v_lshlrev_b32_e32 v235, 16, v235
	v_pk_fma_f32 v[70:71], v[100:101], v[234:235], v[70:71]
	s_waitcnt vmcnt(0)
	v_lshlrev_b32_e32 v244, 16, v244
	v_lshlrev_b32_e32 v245, 16, v245
	v_pk_fma_f32 v[60:61], v[18:19], v[244:245], v[60:61]
	v_lshlrev_b32_e32 v246, 16, v246
	v_lshlrev_b32_e32 v247, 16, v247
	v_pk_fma_f32 v[56:57], v[14:15], v[246:247], v[56:57]
	v_lshlrev_b32_e32 v248, 16, v248
	v_lshlrev_b32_e32 v249, 16, v249
	v_pk_fma_f32 v[54:55], v[10:11], v[248:249], v[54:55]
	v_lshlrev_b32_e32 v250, 16, v250
	v_lshlrev_b32_e32 v251, 16, v251
	v_pk_fma_f32 v[52:53], v[6:7], v[250:251], v[52:53]
	s_add_u32 s8, s8, 0x800
	s_addc_u32 s9, s9, 0
	s_add_u32 s6, s6, 0x100000
	s_addc_u32 s7, s7, 0
	s_cmpk_eq_i32 s8, 0x1800
	s_cbranch_scc1 .LBB0_1717
